# XCD-local barriers use a per-batch flag array (plain store + sc1 poll of 32 flags) instead of counter atomics
# speedup vs baseline: 1.0005x; 1.0005x over previous
; #define LAS __attribute__((address_space(3)))
; __global__ void __launch_bounds__(NTHREADS) fwd_megakernel(Params P) {
;     extern __shared__ __attribute__((aligned(16))) unsigned char lds_raw[];
;     cg::grid_group grid = cg::this_grid();
;     LAS unsigned char* lds = (LAS unsigned char*)lds_raw;
;     unsigned char* ws = P.ws;
;     const int G = gridDim.x, bid = blockIdx.x;
;     volatile LAS unsigned* xb_st = (volatile LAS unsigned*)(lds + LDS_BYTES - 16);
;     if (threadIdx.x == 0) { xb_st[0] = 0u; xb_st[1] = 0u; }
;     __syncthreads();
_Z14fwd_megakernel6Params:
	s_mov_b32 s3, s2
	s_load_dwordx16 s[36:51], s[0:1], 0x40
	s_load_dword s2, s[0:1], 0x88
	s_load_dwordx2 s[24:25], s[0:1], 0x80
	s_add_u32 s4, s0, 0x80
	s_addc_u32 s5, s1, 0
	v_and_b32_e32 v234, 0x3ff, v0
	s_waitcnt lgkmcnt(0)
	v_writelane_b32 v255, s2, 0
	v_writelane_b32 v255, s4, 1
	v_cmp_eq_u32_e64 s[6:7], 0, v234
	s_nop 0
	v_writelane_b32 v255, s5, 2
	s_mov_b64 s[4:5], exec
	v_writelane_b32 v255, s6, 3
	s_nop 1
	v_writelane_b32 v255, s7, 4
	s_and_b64 s[6:7], s[4:5], s[6:7]
	s_mov_b64 exec, s[6:7]
	s_cbranch_execz .LBB0_2
	s_add_i32 s2, 0, 0x267f0
	v_mov_b32_e32 v1, 0
	v_mov_b32_e32 v2, s2
	s_add_i32 s2, 0, 0x267f4
	ds_write_b32 v2, v1
	v_mov_b32_e32 v2, s2
	ds_write_b32 v2, v1
	s_add_i32 s2, 0, 0x267f8
	v_mov_b32_e32 v2, s2
	ds_write_b32 v2, v1

; __device__ __forceinline__ unsigned xb_ld(unsigned* p)              { return __hip_atomic_load(p, __ATOMIC_RELAXED, __HIP_MEMORY_SCOPE_AGENT); }
; __device__ __forceinline__ unsigned xb_add(unsigned* p, unsigned v) { return __hip_atomic_fetch_add(p, v, __ATOMIC_RELAXED, __HIP_MEMORY_SCOPE_AGENT); }
; #define XB_SPIN(cond, bar) do { unsigned _sp = 0; while (cond) { __builtin_amdgcn_s_sleep(1); \
;     if ((++_sp & 255u) == 0u) { if (xb_ld(&(bar)[XB_TMO])) break; if (_sp > XB_SPIN_CAP) { atomicAdd(&(bar)[XB_TMO], 1u); break; } } } } while (0)
; __device__ __forceinline__ void xcd_barrier(const XcdBarrier& b) {
;     asm volatile("s_waitcnt vmcnt(0)" ::: "memory");
;     __syncthreads();
;     if (threadIdx.x == 0) {
;         unsigned* bar = b.bar;
;         __builtin_amdgcn_s_waitcnt(0);
;         unsigned nloc = b.st[0], nx = b.st[1];
;         if (nloc == 0u) { xcd_barrier_complete(bar, b.x, nloc, nx); b.st[0] = nloc; b.st[1] = nx; }
;         const unsigned old = xb_add(&bar[XB_XSUB(b.x)], 1u);
;         const unsigned gen = old / nloc;
;         if (old + 1u == (gen + 1u) * nloc) {
;             __builtin_amdgcn_fence(__ATOMIC_RELEASE, "agent");
;             asm volatile("s_waitcnt vmcnt(0)" ::: "memory");
;             const unsigned og = xb_add(&bar[XB_TOP], 1u);
;             const unsigned tg = og / nx;
;             if (og + 1u == (tg + 1u) * nx) xb_add(&bar[XB_TOPGEN], 1u);
;             else XB_SPIN(xb_ld(&bar[XB_TOPGEN]) == tg, bar);
;             __builtin_amdgcn_fence(__ATOMIC_ACQUIRE, "agent");
;             xb_add(&bar[XB_XGEN(b.x)], 1u);
;             asm volatile("s_waitcnt vmcnt(0)" ::: "memory");
;         } else {
;             XB_SPIN(xb_ld(&bar[XB_XGEN(b.x)]) == gen, bar);
;             __builtin_amdgcn_fence(__ATOMIC_ACQUIRE, "agent");
;             asm volatile("s_waitcnt vmcnt(0)" ::: "memory");
;         }
;     }
;     __syncthreads();
; }
.LBB0_446:
	s_waitcnt vmcnt(0)
	s_waitcnt vmcnt(0) lgkmcnt(0)
	s_barrier
	s_mov_b64 s[0:1], exec
	v_readlane_b32 s4, v255, 3
	v_readlane_b32 s5, v255, 4
	s_and_b64 s[4:5], s[0:1], s[4:5]
	s_xor_b64 s[0:1], s[4:5], s[0:1]
	s_mov_b64 exec, s[4:5]
	s_cbranch_execz .LBB0_499
	s_cmp_lg_u32 s98, 0
	s_cbranch_scc1 .Lfb_old_2
	buffer_inv sc1
	s_and_b32 vcc_lo, s3, 7
	s_lshl_b32 vcc_lo, vcc_lo, 8
	s_add_u32 vcc_lo, vcc_lo, 0x1180480
	s_add_u32 vcc_lo, s50, vcc_lo
	s_addc_u32 vcc_hi, s51, 0
	s_mov_b32 exec_lo, -1
	v_mov_b32_e32 v0, 0x267f8
	s_waitcnt lgkmcnt(0)
	ds_read_b32 v1, v0
	v_mbcnt_lo_u32_b32 v2, -1, 0
	v_lshlrev_b32_e32 v2, 2, v2
	v_add_u32_e32 v2, vcc_lo, v2
	v_mov_b32_e32 v3, vcc_hi
	s_bfe_u32 vcc_lo, s3, 0x50003
	s_waitcnt lgkmcnt(0)
	v_add_u32_e32 v1, 1, v1
	s_lshl_b32 exec_lo, 1, vcc_lo
	ds_write_b32 v0, v1
	global_store_dword v[2:3], v1, off
	s_mov_b32 exec_lo, -1
	v_mov_b32_e32 v5, 0
.Lfb_poll_2:
	global_load_dword v4, v[2:3], off sc1
	s_waitcnt vmcnt(0)
	v_cmp_gt_u32_e32 vcc, v1, v4
	s_cbranch_vccz .Lfb_done_2
	s_sleep 1
	v_add_u32_e32 v5, 1, v5
	v_cmp_gt_u32_e32 vcc, 0x100000, v5
	s_cbranch_vccnz .Lfb_poll_2
.Lfb_done_2:
	s_mov_b32 exec_lo, 1
	s_waitcnt lgkmcnt(0)
	s_branch .LBB0_499
.Lfb_old_2:
	s_add_i32 s2, 0, 0x267f0
	v_mov_b32_e32 v0, s2
	s_waitcnt vmcnt(0) expcnt(0) lgkmcnt(0)
	ds_read_b32 v2, v0
	s_add_i32 s2, 0, 0x267f4
	v_mov_b32_e32 v0, s2
	ds_read_b32 v0, v0
	s_waitcnt lgkmcnt(1)
	v_cmp_ne_u32_e32 vcc, 0, v2
	s_cbranch_vccnz .LBB0_462
	s_add_u32 s4, s50, 0x1180200
	s_addc_u32 s5, s51, 0
	s_add_u32 s6, s50, 0x1180400
	s_addc_u32 s7, s51, 0
	s_add_u32 s8, s50, 0x1180500
	s_addc_u32 s9, s51, 0
	s_add_u32 s10, s50, 0x1180600
	s_addc_u32 s11, s51, 0
	s_add_u32 s12, s50, 0x1180700
	s_addc_u32 s13, s51, 0
	s_add_u32 s14, s50, 0x1180800
	s_addc_u32 s15, s51, 0
	s_add_u32 s16, s50, 0x1180900
	s_addc_u32 s17, s51, 0
	s_add_u32 s18, s50, 0x1180a00
	s_addc_u32 s19, s51, 0
	s_add_u32 s20, s50, 0x1180b00
	s_addc_u32 s21, s51, 0
	s_add_u32 s54, s50, 0x1180c00
	s_addc_u32 s55, s51, 0
	s_add_u32 s56, s50, 0x1180d00
	s_addc_u32 s57, s51, 0
	s_add_u32 s72, s50, 0x1180e00
	s_addc_u32 s73, s51, 0
	s_add_u32 s74, s50, 0x1180f00
	s_addc_u32 s75, s51, 0
	s_add_u32 s76, s50, 0x1181000
	s_addc_u32 s77, s51, 0
	s_add_u32 s78, s50, 0x1181100
	s_addc_u32 s79, s51, 0
	s_add_u32 s80, s50, 0x1181200
	v_readlane_b32 s2, v255, 0
	s_addc_u32 s81, s51, 0
	s_mul_i32 s2, s25, s2
	s_add_u32 s82, s50, 0x1181300
	s_mul_i32 s2, s2, s24
	s_addc_u32 s83, s51, 0
	s_mov_b32 s22, 1
	v_mov_b32_e32 v16, 0
	s_branch .LBB0_450

; __device__ __forceinline__ unsigned xb_add(unsigned* p, unsigned v) { return __hip_atomic_fetch_add(p, v, __ATOMIC_RELAXED, __HIP_MEMORY_SCOPE_AGENT); }
; __device__ __forceinline__ void xcd_barrier(const XcdBarrier& b) {
;     asm volatile("s_waitcnt vmcnt(0)" ::: "memory");
;     __syncthreads();
;     if (threadIdx.x == 0) {
;         unsigned* bar = b.bar;
;         __builtin_amdgcn_s_waitcnt(0);
;         unsigned nloc = b.st[0], nx = b.st[1];
;         if (nloc == 0u) { xcd_barrier_complete(bar, b.x, nloc, nx); b.st[0] = nloc; b.st[1] = nx; }
;         const unsigned old = xb_add(&bar[XB_XSUB(b.x)], 1u);
.LBB0_682:
	s_waitcnt vmcnt(0)
	v_readlane_b32 s4, v255, 3
	v_readlane_b32 s5, v255, 4
	s_barrier
	s_and_saveexec_b64 s[0:1], s[4:5]
	s_xor_b64 s[4:5], exec, s[0:1]
	s_cbranch_execz .LBB0_735
	s_cmp_lg_u32 s98, 0
	s_cbranch_scc1 .Lfb_old_3
	buffer_inv sc1
	s_and_b32 vcc_lo, s3, 7
	s_lshl_b32 vcc_lo, vcc_lo, 8
	s_add_u32 vcc_lo, vcc_lo, 0x1180480
	s_add_u32 vcc_lo, s50, vcc_lo
	s_addc_u32 vcc_hi, s51, 0
	s_mov_b32 exec_lo, -1
	v_mov_b32_e32 v0, 0x267f8
	s_waitcnt lgkmcnt(0)
	ds_read_b32 v1, v0
	v_mbcnt_lo_u32_b32 v2, -1, 0
	v_lshlrev_b32_e32 v2, 2, v2
	v_add_u32_e32 v2, vcc_lo, v2
	v_mov_b32_e32 v3, vcc_hi
	s_bfe_u32 vcc_lo, s3, 0x50003
	s_waitcnt lgkmcnt(0)
	v_add_u32_e32 v1, 1, v1
	s_lshl_b32 exec_lo, 1, vcc_lo
	ds_write_b32 v0, v1
	global_store_dword v[2:3], v1, off
	s_mov_b32 exec_lo, -1
	v_mov_b32_e32 v5, 0

; __device__ __forceinline__ unsigned xb_ld(unsigned* p)              { return __hip_atomic_load(p, __ATOMIC_RELAXED, __HIP_MEMORY_SCOPE_AGENT); }
; __device__ __forceinline__ unsigned xb_add(unsigned* p, unsigned v) { return __hip_atomic_fetch_add(p, v, __ATOMIC_RELAXED, __HIP_MEMORY_SCOPE_AGENT); }
; __device__ __forceinline__ void xcd_barrier_complete(unsigned* bar, unsigned x, unsigned& nloc, unsigned& nx) {
;     const unsigned G = gridDim.x * gridDim.y * gridDim.z;
;     unsigned sum, cnt, mine, sp = 0u;
;     for (;;) {
;         sum = 0u; cnt = 0u; mine = 0u;
; #pragma unroll
;         for (unsigned j = 0; j < 16; ++j) { const unsigned c = xb_ld(&bar[XB_XCNT(j)]); sum += c; cnt += (c > 0u) ? 1u : 0u; mine = (j == x) ? c : mine; }
;         if (sum == G) break;
;         __builtin_amdgcn_s_sleep(1);
;         if ((++sp & 255u) == 0u) { if (xb_ld(&bar[XB_TMO])) break; if (sp > XB_SPIN_CAP) { atomicAdd(&bar[XB_TMO], 1u); break; } }
;     }
;     nloc = mine > 0u ? mine : 1u; nx = cnt > 0u ? cnt : 1u;
; }
; __device__ __forceinline__ void xcd_barrier(const XcdBarrier& b) {
;     asm volatile("s_waitcnt vmcnt(0)" ::: "memory");
;     __syncthreads();
;     if (threadIdx.x == 0) {
;         unsigned* bar = b.bar;
;         __builtin_amdgcn_s_waitcnt(0);
;         unsigned nloc = b.st[0], nx = b.st[1];
;         if (nloc == 0u) { xcd_barrier_complete(bar, b.x, nloc, nx); b.st[0] = nloc; b.st[1] = nx; }
;         const unsigned old = xb_add(&bar[XB_XSUB(b.x)], 1u);
.Lfb_old_3:
	s_add_i32 s0, 0, 0x267f0
	v_mov_b32_e32 v0, s0
	s_waitcnt vmcnt(0) expcnt(0) lgkmcnt(0)
	ds_read_b32 v2, v0
	s_add_i32 s0, 0, 0x267f4
	v_mov_b32_e32 v0, s0
	ds_read_b32 v0, v0
	s_waitcnt lgkmcnt(1)
	v_cmp_ne_u32_e32 vcc, 0, v2
	s_cbranch_vccnz .LBB0_698
	s_add_u32 s6, s50, 0x1180200
	s_addc_u32 s7, s51, 0
	s_add_u32 s8, s50, 0x1180400
	s_addc_u32 s9, s51, 0
	s_add_u32 s10, s50, 0x1180500
	s_addc_u32 s11, s51, 0
	s_add_u32 s12, s50, 0x1180600
	s_addc_u32 s13, s51, 0
	s_add_u32 s14, s50, 0x1180700
	s_addc_u32 s15, s51, 0
	s_add_u32 s16, s50, 0x1180800
	s_addc_u32 s17, s51, 0
	s_add_u32 s18, s50, 0x1180900
	s_addc_u32 s19, s51, 0
	s_add_u32 s20, s50, 0x1180a00
	s_addc_u32 s21, s51, 0
	s_add_u32 s58, s50, 0x1180b00
	s_addc_u32 s59, s51, 0
	s_add_u32 s60, s50, 0x1180c00
	s_addc_u32 s61, s51, 0
	s_add_u32 s62, s50, 0x1180d00
	s_addc_u32 s63, s51, 0
	s_add_u32 s64, s50, 0x1180e00
	s_addc_u32 s65, s51, 0
	s_add_u32 s66, s50, 0x1180f00
	s_addc_u32 s67, s51, 0
	s_add_u32 s68, s50, 0x1181000
	s_addc_u32 s69, s51, 0
	s_add_u32 s70, s50, 0x1181100
	s_addc_u32 s71, s51, 0
	s_add_u32 s72, s50, 0x1181200
	v_readlane_b32 s0, v255, 0
	s_addc_u32 s73, s51, 0
	s_mul_i32 s0, s25, s0
	s_add_u32 s74, s50, 0x1181300
	s_mul_i32 s0, s0, s24
	s_addc_u32 s75, s51, 0
	s_mov_b32 s1, 1
	v_mov_b32_e32 v16, 0
	s_branch .LBB0_686

; __device__ __forceinline__ unsigned xb_add(unsigned* p, unsigned v) { return __hip_atomic_fetch_add(p, v, __ATOMIC_RELAXED, __HIP_MEMORY_SCOPE_AGENT); }
; __device__ __forceinline__ void xcd_barrier(const XcdBarrier& b) {
;     asm volatile("s_waitcnt vmcnt(0)" ::: "memory");
;     __syncthreads();
;     if (threadIdx.x == 0) {
;         unsigned* bar = b.bar;
;         __builtin_amdgcn_s_waitcnt(0);
;         unsigned nloc = b.st[0], nx = b.st[1];
;         if (nloc == 0u) { xcd_barrier_complete(bar, b.x, nloc, nx); b.st[0] = nloc; b.st[1] = nx; }
;         const unsigned old = xb_add(&bar[XB_XSUB(b.x)], 1u);
.LBB0_773:
	s_waitcnt vmcnt(0)
	s_waitcnt lgkmcnt(0)
	s_barrier
	s_mov_b64 s[0:1], exec
	v_readlane_b32 s4, v255, 3
	v_readlane_b32 s5, v255, 4
	s_and_b64 s[4:5], s[0:1], s[4:5]
	s_xor_b64 s[0:1], s[4:5], s[0:1]
	s_mov_b64 exec, s[4:5]
	s_cbranch_execz .LBB0_826
	s_cmp_lg_u32 s98, 0
	s_cbranch_scc1 .Lfb_old_4
	buffer_inv sc1
	s_and_b32 vcc_lo, s3, 7
	s_lshl_b32 vcc_lo, vcc_lo, 8
	s_add_u32 vcc_lo, vcc_lo, 0x1180480
	s_add_u32 vcc_lo, s50, vcc_lo
	s_addc_u32 vcc_hi, s51, 0
	s_mov_b32 exec_lo, -1
	v_mov_b32_e32 v0, 0x267f8
	s_waitcnt lgkmcnt(0)
	ds_read_b32 v1, v0
	v_mbcnt_lo_u32_b32 v2, -1, 0
	v_lshlrev_b32_e32 v2, 2, v2
	v_add_u32_e32 v2, vcc_lo, v2
	v_mov_b32_e32 v3, vcc_hi
	s_bfe_u32 vcc_lo, s3, 0x50003
	s_waitcnt lgkmcnt(0)
	v_add_u32_e32 v1, 1, v1
	s_lshl_b32 exec_lo, 1, vcc_lo
	ds_write_b32 v0, v1
	global_store_dword v[2:3], v1, off
	s_mov_b32 exec_lo, -1
	v_mov_b32_e32 v5, 0

; __device__ __forceinline__ unsigned xb_ld(unsigned* p)              { return __hip_atomic_load(p, __ATOMIC_RELAXED, __HIP_MEMORY_SCOPE_AGENT); }
; __device__ __forceinline__ unsigned xb_add(unsigned* p, unsigned v) { return __hip_atomic_fetch_add(p, v, __ATOMIC_RELAXED, __HIP_MEMORY_SCOPE_AGENT); }
; __device__ __forceinline__ void xcd_barrier_complete(unsigned* bar, unsigned x, unsigned& nloc, unsigned& nx) {
;     const unsigned G = gridDim.x * gridDim.y * gridDim.z;
;     unsigned sum, cnt, mine, sp = 0u;
;     for (;;) {
;         sum = 0u; cnt = 0u; mine = 0u;
; #pragma unroll
;         for (unsigned j = 0; j < 16; ++j) { const unsigned c = xb_ld(&bar[XB_XCNT(j)]); sum += c; cnt += (c > 0u) ? 1u : 0u; mine = (j == x) ? c : mine; }
;         if (sum == G) break;
;         __builtin_amdgcn_s_sleep(1);
;         if ((++sp & 255u) == 0u) { if (xb_ld(&bar[XB_TMO])) break; if (sp > XB_SPIN_CAP) { atomicAdd(&bar[XB_TMO], 1u); break; } }
;     }
;     nloc = mine > 0u ? mine : 1u; nx = cnt > 0u ? cnt : 1u;
; }
; __device__ __forceinline__ void xcd_barrier(const XcdBarrier& b) {
;     asm volatile("s_waitcnt vmcnt(0)" ::: "memory");
;     __syncthreads();
;     if (threadIdx.x == 0) {
;         unsigned* bar = b.bar;
;         __builtin_amdgcn_s_waitcnt(0);
;         unsigned nloc = b.st[0], nx = b.st[1];
;         if (nloc == 0u) { xcd_barrier_complete(bar, b.x, nloc, nx); b.st[0] = nloc; b.st[1] = nx; }
;         const unsigned old = xb_add(&bar[XB_XSUB(b.x)], 1u);
.Lfb_old_4:
	s_add_i32 s2, 0, 0x267f0
	v_mov_b32_e32 v0, s2
	s_waitcnt vmcnt(0) expcnt(0) lgkmcnt(0)
	ds_read_b32 v2, v0
	s_add_i32 s2, 0, 0x267f4
	v_mov_b32_e32 v0, s2
	ds_read_b32 v0, v0
	s_waitcnt lgkmcnt(1)
	v_cmp_ne_u32_e32 vcc, 0, v2
	s_cbranch_vccnz .LBB0_789
	s_add_u32 s4, s50, 0x1180200
	s_addc_u32 s5, s51, 0
	s_add_u32 s8, s50, 0x1180400
	s_addc_u32 s9, s51, 0
	s_add_u32 s10, s50, 0x1180500
	s_addc_u32 s11, s51, 0
	s_add_u32 s12, s50, 0x1180600
	s_addc_u32 s13, s51, 0
	s_add_u32 s14, s50, 0x1180700
	s_addc_u32 s15, s51, 0
	s_add_u32 s16, s50, 0x1180800
	s_addc_u32 s17, s51, 0
	s_add_u32 s18, s50, 0x1180900
	s_addc_u32 s19, s51, 0
	s_add_u32 s20, s50, 0x1180a00
	s_addc_u32 s21, s51, 0
	s_add_u32 s46, s50, 0x1180b00
	s_addc_u32 s47, s51, 0
	s_add_u32 s52, s50, 0x1180c00
	s_addc_u32 s53, s51, 0
	s_add_u32 s58, s50, 0x1180d00
	s_addc_u32 s59, s51, 0
	s_add_u32 s60, s50, 0x1180e00
	s_addc_u32 s61, s51, 0
	s_add_u32 s62, s50, 0x1180f00
	s_addc_u32 s63, s51, 0
	s_add_u32 s64, s50, 0x1181000
	s_addc_u32 s65, s51, 0
	s_add_u32 s66, s50, 0x1181100
	s_addc_u32 s67, s51, 0
	s_add_u32 s68, s50, 0x1181200
	v_readlane_b32 s2, v255, 0
	s_addc_u32 s69, s51, 0
	s_mul_i32 s2, s25, s2
	s_add_u32 s70, s50, 0x1181300
	s_mul_i32 s2, s2, s24
	s_addc_u32 s71, s51, 0
	s_mov_b32 s22, 1
	v_mov_b32_e32 v16, 0
	s_branch .LBB0_777

; __device__ __forceinline__ unsigned xb_add(unsigned* p, unsigned v) { return __hip_atomic_fetch_add(p, v, __ATOMIC_RELAXED, __HIP_MEMORY_SCOPE_AGENT); }
; __device__ __forceinline__ void xcd_barrier(const XcdBarrier& b) {
;     asm volatile("s_waitcnt vmcnt(0)" ::: "memory");
;     __syncthreads();
;     if (threadIdx.x == 0) {
;         unsigned* bar = b.bar;
;         __builtin_amdgcn_s_waitcnt(0);
;         unsigned nloc = b.st[0], nx = b.st[1];
;         if (nloc == 0u) { xcd_barrier_complete(bar, b.x, nloc, nx); b.st[0] = nloc; b.st[1] = nx; }
;         const unsigned old = xb_add(&bar[XB_XSUB(b.x)], 1u);
.LBB0_855:
	v_writelane_b32 v255, s10, 32
	v_writelane_b32 v255, s11, 33
	v_writelane_b32 v255, s18, 34
	v_writelane_b32 v255, s19, 35
	v_writelane_b32 v255, s20, 36
	v_writelane_b32 v255, s21, 37
	v_writelane_b32 v255, s34, 38
	v_writelane_b32 v255, s35, 39
	s_waitcnt vmcnt(0)
	s_barrier
	s_mov_b64 s[0:1], exec
	v_readlane_b32 s4, v255, 3
	v_readlane_b32 s5, v255, 4
	s_and_b64 s[4:5], s[0:1], s[4:5]
	s_xor_b64 s[0:1], s[4:5], s[0:1]
	s_mov_b64 exec, s[4:5]
	s_cbranch_execz .LBB0_908
	s_cmp_lg_u32 s98, 0
	s_cbranch_scc1 .Lfb_old_5
	buffer_inv sc1
	s_and_b32 vcc_lo, s3, 7
	s_lshl_b32 vcc_lo, vcc_lo, 8
	s_add_u32 vcc_lo, vcc_lo, 0x1180480
	s_add_u32 vcc_lo, s50, vcc_lo
	s_addc_u32 vcc_hi, s51, 0
	s_mov_b32 exec_lo, -1
	v_mov_b32_e32 v0, 0x267f8
	s_waitcnt lgkmcnt(0)
	ds_read_b32 v1, v0
	v_mbcnt_lo_u32_b32 v2, -1, 0
	v_lshlrev_b32_e32 v2, 2, v2
	v_add_u32_e32 v2, vcc_lo, v2
	v_mov_b32_e32 v3, vcc_hi
	s_bfe_u32 vcc_lo, s3, 0x50003
	s_waitcnt lgkmcnt(0)
	v_add_u32_e32 v1, 1, v1
	s_lshl_b32 exec_lo, 1, vcc_lo
	ds_write_b32 v0, v1
	global_store_dword v[2:3], v1, off
	s_mov_b32 exec_lo, -1
	v_mov_b32_e32 v5, 0

; __device__ __forceinline__ unsigned xb_ld(unsigned* p)              { return __hip_atomic_load(p, __ATOMIC_RELAXED, __HIP_MEMORY_SCOPE_AGENT); }
; __device__ __forceinline__ unsigned xb_add(unsigned* p, unsigned v) { return __hip_atomic_fetch_add(p, v, __ATOMIC_RELAXED, __HIP_MEMORY_SCOPE_AGENT); }
; __device__ __forceinline__ void xcd_barrier_complete(unsigned* bar, unsigned x, unsigned& nloc, unsigned& nx) {
;     const unsigned G = gridDim.x * gridDim.y * gridDim.z;
;     unsigned sum, cnt, mine, sp = 0u;
;     for (;;) {
;         sum = 0u; cnt = 0u; mine = 0u;
; #pragma unroll
;         for (unsigned j = 0; j < 16; ++j) { const unsigned c = xb_ld(&bar[XB_XCNT(j)]); sum += c; cnt += (c > 0u) ? 1u : 0u; mine = (j == x) ? c : mine; }
;         if (sum == G) break;
;         __builtin_amdgcn_s_sleep(1);
;         if ((++sp & 255u) == 0u) { if (xb_ld(&bar[XB_TMO])) break; if (sp > XB_SPIN_CAP) { atomicAdd(&bar[XB_TMO], 1u); break; } }
;     }
;     nloc = mine > 0u ? mine : 1u; nx = cnt > 0u ? cnt : 1u;
; }
; __device__ __forceinline__ void xcd_barrier(const XcdBarrier& b) {
;     asm volatile("s_waitcnt vmcnt(0)" ::: "memory");
;     __syncthreads();
;     if (threadIdx.x == 0) {
;         unsigned* bar = b.bar;
;         __builtin_amdgcn_s_waitcnt(0);
;         unsigned nloc = b.st[0], nx = b.st[1];
;         if (nloc == 0u) { xcd_barrier_complete(bar, b.x, nloc, nx); b.st[0] = nloc; b.st[1] = nx; }
;         const unsigned old = xb_add(&bar[XB_XSUB(b.x)], 1u);
.Lfb_old_5:
	s_add_i32 s2, 0, 0x267f0
	v_mov_b32_e32 v0, s2
	s_waitcnt vmcnt(0) expcnt(0) lgkmcnt(0)
	ds_read_b32 v2, v0
	s_add_i32 s2, 0, 0x267f4
	v_mov_b32_e32 v0, s2
	ds_read_b32 v0, v0
	s_waitcnt lgkmcnt(1)
	v_cmp_ne_u32_e32 vcc, 0, v2
	s_cbranch_vccnz .LBB0_871
	s_add_u32 s4, s50, 0x1180200
	s_addc_u32 s5, s51, 0
	s_add_u32 s6, s50, 0x1180400
	s_addc_u32 s7, s51, 0
	s_add_u32 s8, s50, 0x1180500
	s_addc_u32 s9, s51, 0
	s_add_u32 s12, s50, 0x1180600
	s_addc_u32 s13, s51, 0
	s_add_u32 s14, s50, 0x1180700
	s_addc_u32 s15, s51, 0
	s_add_u32 s16, s50, 0x1180800
	s_addc_u32 s17, s51, 0
	s_add_u32 s18, s50, 0x1180900
	s_addc_u32 s19, s51, 0
	s_add_u32 s20, s50, 0x1180a00
	s_addc_u32 s21, s51, 0
	s_add_u32 s34, s50, 0x1180b00
	s_addc_u32 s35, s51, 0
	s_add_u32 s40, s50, 0x1180c00
	s_addc_u32 s41, s51, 0
	s_add_u32 s42, s50, 0x1180d00
	s_addc_u32 s43, s51, 0
	s_add_u32 s44, s50, 0x1180e00
	s_addc_u32 s45, s51, 0
	s_add_u32 s46, s50, 0x1180f00
	s_addc_u32 s47, s51, 0
	s_add_u32 s52, s50, 0x1181000
	s_addc_u32 s53, s51, 0
	s_add_u32 s58, s50, 0x1181100
	s_addc_u32 s59, s51, 0
	s_add_u32 s60, s50, 0x1181200
	v_readlane_b32 s2, v255, 0
	s_addc_u32 s61, s51, 0
	s_mul_i32 s2, s25, s2
	s_add_u32 s62, s50, 0x1181300
	s_mul_i32 s2, s2, s24
	s_addc_u32 s63, s51, 0
	s_mov_b32 s22, 1
	v_mov_b32_e32 v16, 0
	s_branch .LBB0_859

; __device__ __forceinline__ unsigned xb_add(unsigned* p, unsigned v) { return __hip_atomic_fetch_add(p, v, __ATOMIC_RELAXED, __HIP_MEMORY_SCOPE_AGENT); }
; __device__ __forceinline__ void xcd_barrier(const XcdBarrier& b) {
;     asm volatile("s_waitcnt vmcnt(0)" ::: "memory");
;     __syncthreads();
;     if (threadIdx.x == 0) {
;         unsigned* bar = b.bar;
;         __builtin_amdgcn_s_waitcnt(0);
;         unsigned nloc = b.st[0], nx = b.st[1];
;         if (nloc == 0u) { xcd_barrier_complete(bar, b.x, nloc, nx); b.st[0] = nloc; b.st[1] = nx; }
;         const unsigned old = xb_add(&bar[XB_XSUB(b.x)], 1u);
.Lb3_done:
	s_waitcnt vmcnt(0)
	s_barrier
	s_mov_b64 s[0:1], exec
	v_readlane_b32 s4, v255, 3
	v_readlane_b32 s5, v255, 4
	s_and_b64 s[4:5], s[0:1], s[4:5]
	s_mov_b64 exec, s[4:5]
	s_cbranch_execz .LBB0_980
	s_cmp_lg_u32 s98, 0
	s_cbranch_scc1 .Lfb_old_6
	buffer_inv sc1
	s_and_b32 vcc_lo, s3, 7
	s_lshl_b32 vcc_lo, vcc_lo, 8
	s_add_u32 vcc_lo, vcc_lo, 0x1180480
	s_add_u32 vcc_lo, s50, vcc_lo
	s_addc_u32 vcc_hi, s51, 0
	s_mov_b32 exec_lo, -1
	v_mov_b32_e32 v0, 0x267f8
	s_waitcnt lgkmcnt(0)
	ds_read_b32 v1, v0
	v_mbcnt_lo_u32_b32 v2, -1, 0
	v_lshlrev_b32_e32 v2, 2, v2
	v_add_u32_e32 v2, vcc_lo, v2
	v_mov_b32_e32 v3, vcc_hi
	s_bfe_u32 vcc_lo, s3, 0x50003
	s_waitcnt lgkmcnt(0)
	v_add_u32_e32 v1, 1, v1
	s_lshl_b32 exec_lo, 1, vcc_lo
	ds_write_b32 v0, v1
	global_store_dword v[2:3], v1, off
	s_mov_b32 exec_lo, -1
	v_mov_b32_e32 v5, 0

; __device__ __forceinline__ unsigned xb_ld(unsigned* p)              { return __hip_atomic_load(p, __ATOMIC_RELAXED, __HIP_MEMORY_SCOPE_AGENT); }
; __device__ __forceinline__ unsigned xb_add(unsigned* p, unsigned v) { return __hip_atomic_fetch_add(p, v, __ATOMIC_RELAXED, __HIP_MEMORY_SCOPE_AGENT); }
; __device__ __forceinline__ void xcd_barrier_complete(unsigned* bar, unsigned x, unsigned& nloc, unsigned& nx) {
;     const unsigned G = gridDim.x * gridDim.y * gridDim.z;
;     unsigned sum, cnt, mine, sp = 0u;
;     for (;;) {
;         sum = 0u; cnt = 0u; mine = 0u;
; #pragma unroll
;         for (unsigned j = 0; j < 16; ++j) { const unsigned c = xb_ld(&bar[XB_XCNT(j)]); sum += c; cnt += (c > 0u) ? 1u : 0u; mine = (j == x) ? c : mine; }
;         if (sum == G) break;
;         __builtin_amdgcn_s_sleep(1);
;         if ((++sp & 255u) == 0u) { if (xb_ld(&bar[XB_TMO])) break; if (sp > XB_SPIN_CAP) { atomicAdd(&bar[XB_TMO], 1u); break; } }
;     }
;     nloc = mine > 0u ? mine : 1u; nx = cnt > 0u ? cnt : 1u;
; }
; __device__ __forceinline__ void xcd_barrier(const XcdBarrier& b) {
;     asm volatile("s_waitcnt vmcnt(0)" ::: "memory");
;     __syncthreads();
;     if (threadIdx.x == 0) {
;         unsigned* bar = b.bar;
;         __builtin_amdgcn_s_waitcnt(0);
;         unsigned nloc = b.st[0], nx = b.st[1];
;         if (nloc == 0u) { xcd_barrier_complete(bar, b.x, nloc, nx); b.st[0] = nloc; b.st[1] = nx; }
;         const unsigned old = xb_add(&bar[XB_XSUB(b.x)], 1u);
.Lfb_old_6:
	s_add_i32 s2, 0, 0x267f0
	v_mov_b32_e32 v0, s2
	s_waitcnt vmcnt(0) expcnt(0) lgkmcnt(0)
	ds_read_b32 v2, v0
	s_add_i32 s2, 0, 0x267f4
	v_mov_b32_e32 v0, s2
	ds_read_b32 v0, v0
	s_waitcnt lgkmcnt(1)
	v_cmp_ne_u32_e32 vcc, 0, v2
	s_cbranch_vccnz .LBB0_944
	s_add_u32 s4, s50, 0x1180200
	s_addc_u32 s5, s51, 0
	s_add_u32 s6, s50, 0x1180400
	s_addc_u32 s7, s51, 0
	s_add_u32 s8, s50, 0x1180500
	s_addc_u32 s9, s51, 0
	s_add_u32 s10, s50, 0x1180600
	s_addc_u32 s11, s51, 0
	s_add_u32 s12, s50, 0x1180700
	s_addc_u32 s13, s51, 0
	s_add_u32 s14, s50, 0x1180800
	s_addc_u32 s15, s51, 0
	s_add_u32 s16, s50, 0x1180900
	s_addc_u32 s17, s51, 0
	s_add_u32 s18, s50, 0x1180a00
	s_addc_u32 s19, s51, 0
	s_add_u32 s20, s50, 0x1180b00
	s_addc_u32 s21, s51, 0
	s_add_u32 s22, s50, 0x1180c00
	s_addc_u32 s23, s51, 0
	s_add_u32 s34, s50, 0x1180d00
	s_addc_u32 s35, s51, 0
	s_add_u32 s36, s50, 0x1180e00
	s_addc_u32 s37, s51, 0
	s_add_u32 s38, s50, 0x1180f00
	s_addc_u32 s39, s51, 0
	s_add_u32 s40, s50, 0x1181000
	s_addc_u32 s41, s51, 0
	s_add_u32 s42, s50, 0x1181100
	s_addc_u32 s43, s51, 0
	s_add_u32 s44, s50, 0x1181200
	v_readlane_b32 s2, v255, 0
	s_addc_u32 s45, s51, 0
	s_mul_i32 s2, s25, s2
	s_add_u32 s46, s50, 0x1181300
	s_mul_i32 s2, s2, s24
	s_addc_u32 s47, s51, 0
	s_mov_b32 s25, 1
	v_mov_b32_e32 v16, 0
	s_branch .LBB0_932
